# v12 + FFN-in fast-path silu: packed -log2e scale from SGPR pair, (t*up)*rcp ordering (8 fewer VALU per 8 outputs)
# speedup vs baseline: 1.0117x; 1.0043x over previous
; DI void stf8(float* p, const F8& f) { *(float4*)p = make_float4(f.v[0], f.v[1], f.v[2], f.v[3]); *(float4*)(p + 4) = make_float4(f.v[4], f.v[5], f.v[6], f.v[7]); }
; DI void stb8(bf16_t* p, const F8& f) { *(uint4*)p = pack8(f); }
; DI float siluf(float x) { return x / (1.f + __expf(-x)); }
; template <int MODE>
; DI void gemm_epilogue(const float* Cs, int m0, int n0, const Epi& ep) {
;     ...
;         const int mt = m0 >> 7, ch0 = (n0 >> 7) * 64, c8 = (tid & 7) * 8, ch = ch0 + c8;
;         const float* cw = ep.c0;
;         const F8 w0 = ldf8(cw + ch), w1 = ldf8(cw + 2816 + ch), w2 = ldf8(cw + 2 * 2816 + ch);
;         const bool defer01 = (m0 < MP) && ((m0 & 8191) != 0);
; #pragma unroll
;         for (int it = 0; it < 2; ++it) {
;             const int i = (tid >> 3) + 64 * it, r = m0 + i;
;             int sq, pos, len; rowinfo(r, sq, pos, len);
;             const F8 g0 = ldf8(Cs + i * LDC + c8), up = ldf8(Cs + i * LDC + 64 + c8);
;             if (i >= 126) stf8(ep.f0 + ((size_t)mt * 2 + (i - 126)) * 2816 + ch, g0);
;             if (i < 2) { stf8(ep.f1 + ((size_t)mt * 2 + i) * 2816 + ch, g0); stf8(ep.f2 + ((size_t)mt * 2 + i) * 2816 + ch, up); }
;             if (pos >= len - 2) {
;                 float* so = sq < 4 ? ep.out + O_PFF + (((size_t)ep.layer * 4 + sq) * 2 + (pos - (len - 2))) * 2816
;                                    : ep.out + O_SFF + (((size_t)ep.layer * 8 + (sq - 4)) * 2 + (pos - (len - 2))) * 2816;
;                 stf8(so + ch, g0);
;             }
;             if (i < 2 && defer01) continue;
;             F8 g1, g2;
;             const float* hist = sq >= 4 ? ep.c1 + ((size_t)ep.layer * 8 + (sq - 4)) * 2 * 2816 + ch : nullptr;
;             if (pos >= 1) g1 = ldf8(Cs + (i - 1) * LDC + c8);
;             else if (hist) g1 = ldf8(hist + 2816);
;             else { for (int e = 0; e < 8; ++e) g1.v[e] = 0.f; }
;             if (pos >= 2) g2 = ldf8(Cs + (i - 2) * LDC + c8);
;             else if (hist) g2 = ldf8(hist + (size_t)pos * 2816);
;             else { for (int e = 0; e < 8; ++e) g2.v[e] = 0.f; }
;             F8 o;
; #pragma unroll
;             for (int e = 0; e < 8; ++e) o.v[e] = siluf(w0.v[e] * g2.v[e] + w1.v[e] * g1.v[e] + w2.v[e] * g0.v[e]) * up.v[e];
;             stb8(ep.b0 + (size_t)r * 2816 + ch, o);
.Lffn_fast:
	s_lshl_b32 s54, s27, 8
	s_lshl_b32 s30, s26, 7
	s_lshl_b32 s31, s27, 2
	v_lshrrev_b32_e32 v195, 3, v250
	v_and_b32_e32 v212, 7, v250
	v_lshlrev_b32_e32 v212, 3, v212
	v_add_u32_e32 v64, s30, v212
	v_add_u32_e32 v65, s54, v195
	s_movk_i32 s0, 0x1600
	v_add_u32_e32 v66, s31, v195
	v_mul_lo_u32 v65, v65, s0
	v_mul_lo_u32 v66, v66, s3
	v_mul_u32_u24_e32 v197, 0x210, v195
	v_lshl_add_u32 v65, v64, 1, v65
	v_lshlrev_b32_e32 v64, 2, v64
	v_lshl_add_u32 v67, v212, 2, 16
	v_add_u32_e32 v66, v66, v64
	v_add_u32_e32 v197, v197, v67
	v_cmp_lt_u32_e64 s[40:41], 1, v195
	v_cmp_gt_u32_e64 s[42:43], 2, v195
	v_cmp_lt_u32_e64 s[44:45], 61, v195
	v_add_u32_e32 v196, 0xfffffbe0, v197
	v_max_i32_e32 v196, v196, v67
	s_mov_b32 s30, 0xbfb8aa3b
	s_mov_b32 s31, 0xbfb8aa3b
	global_load_dwordx4 v[128:131], v64, s[6:7] offset:0
	global_load_dwordx4 v[132:135], v64, s[6:7] offset:16
	global_load_dwordx4 v[136:139], v64, s[14:15] offset:0
	global_load_dwordx4 v[140:143], v64, s[14:15] offset:16
	global_load_dwordx4 v[144:147], v64, s[18:19] offset:0
	global_load_dwordx4 v[148:151], v64, s[18:19] offset:16
	ds_write_b128 v194, v[96:99]
	ds_write_b128 v194, v[100:103] offset:64
	ds_write_b128 v194, v[104:107] offset:8448
	ds_write_b128 v194, v[108:111] offset:8512
	ds_write_b128 v194, v[112:115] offset:16896
	ds_write_b128 v194, v[116:119] offset:16960
	ds_write_b128 v194, v[120:123] offset:25344
	ds_write_b128 v194, v[124:127] offset:25408
	s_waitcnt lgkmcnt(0)
	s_barrier
	ds_read_b128 v[96:99], v197
	ds_read_b128 v[100:103], v197 offset:16
	ds_read_b128 v[104:107], v197 offset:256
	ds_read_b128 v[108:111], v197 offset:272
	ds_read_b128 v[112:115], v196 offset:528
	ds_read_b128 v[116:119], v196 offset:544
	ds_read_b128 v[120:123], v196
	ds_read_b128 v[124:127], v196 offset:16
	s_waitcnt vmcnt(0)
	s_mov_b64 exec, s[42:43]
	s_cbranch_execz .Lffn_f1
	s_waitcnt lgkmcnt(4)
	global_store_dwordx4 v66, v[96:99], s[80:81] offset:0
	global_store_dwordx4 v66, v[100:103], s[80:81] offset:16
	global_store_dwordx4 v66, v[104:107], s[82:83] offset:0
	global_store_dwordx4 v66, v[108:111], s[82:83] offset:16
.Lffn_f1:
	s_mov_b64 exec, -1
	s_waitcnt lgkmcnt(0)
	v_pk_mul_f32 v[120:121], v[128:129], v[120:121]
	v_pk_mul_f32 v[122:123], v[130:131], v[122:123]
	v_pk_mul_f32 v[124:125], v[132:133], v[124:125]
	v_pk_mul_f32 v[126:127], v[134:135], v[126:127]
	v_pk_fma_f32 v[120:121], v[136:137], v[112:113], v[120:121]
	v_pk_fma_f32 v[122:123], v[138:139], v[114:115], v[122:123]
	v_pk_fma_f32 v[124:125], v[140:141], v[116:117], v[124:125]
	v_pk_fma_f32 v[126:127], v[142:143], v[118:119], v[126:127]
	v_pk_fma_f32 v[120:121], v[144:145], v[96:97], v[120:121]
	v_pk_fma_f32 v[122:123], v[146:147], v[98:99], v[122:123]
	v_pk_fma_f32 v[124:125], v[148:149], v[100:101], v[124:125]
	v_pk_fma_f32 v[126:127], v[150:151], v[102:103], v[126:127]
	v_pk_mul_f32 v[152:153], v[120:121], s[30:31]
	v_pk_mul_f32 v[154:155], v[122:123], s[30:31]
	v_pk_mul_f32 v[164:165], v[124:125], s[30:31]
	v_pk_mul_f32 v[166:167], v[126:127], s[30:31]
	v_pk_mul_f32 v[120:121], v[104:105], v[120:121]
	v_pk_mul_f32 v[122:123], v[106:107], v[122:123]
	v_pk_mul_f32 v[124:125], v[108:109], v[124:125]
	v_pk_mul_f32 v[126:127], v[110:111], v[126:127]
	v_exp_f32_e32 v152, v152
	v_exp_f32_e32 v153, v153
	v_exp_f32_e32 v154, v154
	v_exp_f32_e32 v155, v155
	v_exp_f32_e32 v164, v164
	v_exp_f32_e32 v165, v165
	v_exp_f32_e32 v166, v166
	v_exp_f32_e32 v167, v167
	v_pk_add_f32 v[152:153], v[152:153], 1.0 op_sel_hi:[1,0]
	v_pk_add_f32 v[154:155], v[154:155], 1.0 op_sel_hi:[1,0]
	v_pk_add_f32 v[164:165], v[164:165], 1.0 op_sel_hi:[1,0]
	v_pk_add_f32 v[166:167], v[166:167], 1.0 op_sel_hi:[1,0]
	v_rcp_f32_e32 v152, v152
	v_rcp_f32_e32 v153, v153
	v_rcp_f32_e32 v154, v154
	v_rcp_f32_e32 v155, v155
	v_rcp_f32_e32 v164, v164
	v_rcp_f32_e32 v165, v165
	v_rcp_f32_e32 v166, v166
	v_rcp_f32_e32 v167, v167
	v_pk_mul_f32 v[120:121], v[120:121], v[152:153]
	v_pk_mul_f32 v[122:123], v[122:123], v[154:155]
	v_pk_mul_f32 v[124:125], v[124:125], v[164:165]
	v_pk_mul_f32 v[126:127], v[126:127], v[166:167]
	v_cvt_pk_bf16_f32 v152, v120, v121
	v_cvt_pk_bf16_f32 v153, v122, v123
	v_cvt_pk_bf16_f32 v154, v124, v125
	v_cvt_pk_bf16_f32 v155, v126, v127
	s_mov_b64 exec, s[40:41]
	global_store_dwordx4 v65, v[152:155], s[84:85] offset:0
	s_mov_b64 exec, -1
	ds_read_b128 v[96:99], v197 offset:33792
	ds_read_b128 v[100:103], v197 offset:33808
	ds_read_b128 v[104:107], v197 offset:34048
	ds_read_b128 v[108:111], v197 offset:34064
	ds_read_b128 v[112:115], v197 offset:33264
	ds_read_b128 v[116:119], v197 offset:33280
	ds_read_b128 v[120:123], v197 offset:32736
	ds_read_b128 v[124:127], v197 offset:32752
	v_add_u32_e32 v67, 0x58000, v65
	s_mov_b64 exec, s[44:45]
	s_cbranch_execz .Lffn_f2
	v_add_u32_e32 v212, 0xfff55800, v66
	s_waitcnt lgkmcnt(6)
	global_store_dwordx4 v212, v[96:99], s[72:73] offset:0
	global_store_dwordx4 v212, v[100:103], s[72:73] offset:16
; DI void stf8(float* p, const F8& f) { *(float4*)p = make_float4(f.v[0], f.v[1], f.v[2], f.v[3]); *(float4*)(p + 4) = make_float4(f.v[4], f.v[5], f.v[6], f.v[7]); }
; DI void stb8(bf16_t* p, const F8& f) { *(uint4*)p = pack8(f); }
; DI float siluf(float x) { return x / (1.f + __expf(-x)); }
; template <int MODE>
; DI void gemm_epilogue(const float* Cs, int m0, int n0, const Epi& ep) {
;     ...
;         const int mt = m0 >> 7, ch0 = (n0 >> 7) * 64, c8 = (tid & 7) * 8, ch = ch0 + c8;
;         const float* cw = ep.c0;
;         const F8 w0 = ldf8(cw + ch), w1 = ldf8(cw + 2816 + ch), w2 = ldf8(cw + 2 * 2816 + ch);
;         const bool defer01 = (m0 < MP) && ((m0 & 8191) != 0);
; #pragma unroll
;         for (int it = 0; it < 2; ++it) {
;             const int i = (tid >> 3) + 64 * it, r = m0 + i;
;             int sq, pos, len; rowinfo(r, sq, pos, len);
;             const F8 g0 = ldf8(Cs + i * LDC + c8), up = ldf8(Cs + i * LDC + 64 + c8);
;             if (i >= 126) stf8(ep.f0 + ((size_t)mt * 2 + (i - 126)) * 2816 + ch, g0);
;             if (i < 2) { stf8(ep.f1 + ((size_t)mt * 2 + i) * 2816 + ch, g0); stf8(ep.f2 + ((size_t)mt * 2 + i) * 2816 + ch, up); }
;             if (pos >= len - 2) {
;                 float* so = sq < 4 ? ep.out + O_PFF + (((size_t)ep.layer * 4 + sq) * 2 + (pos - (len - 2))) * 2816
;                                    : ep.out + O_SFF + (((size_t)ep.layer * 8 + (sq - 4)) * 2 + (pos - (len - 2))) * 2816;
;                 stf8(so + ch, g0);
;             }
;             if (i < 2 && defer01) continue;
;             F8 g1, g2;
;             const float* hist = sq >= 4 ? ep.c1 + ((size_t)ep.layer * 8 + (sq - 4)) * 2 * 2816 + ch : nullptr;
;             if (pos >= 1) g1 = ldf8(Cs + (i - 1) * LDC + c8);
;             else if (hist) g1 = ldf8(hist + 2816);
;             else { for (int e = 0; e < 8; ++e) g1.v[e] = 0.f; }
;             if (pos >= 2) g2 = ldf8(Cs + (i - 2) * LDC + c8);
;             else if (hist) g2 = ldf8(hist + (size_t)pos * 2816);
;             else { for (int e = 0; e < 8; ++e) g2.v[e] = 0.f; }
;             F8 o;
; #pragma unroll
;             for (int e = 0; e < 8; ++e) o.v[e] = siluf(w0.v[e] * g2.v[e] + w1.v[e] * g1.v[e] + w2.v[e] * g0.v[e]) * up.v[e];
;             stb8(ep.b0 + (size_t)r * 2816 + ch, o);
.Lffn_f2:
	s_mov_b64 exec, -1
	s_waitcnt lgkmcnt(0)
	v_pk_mul_f32 v[120:121], v[128:129], v[120:121]
	v_pk_mul_f32 v[122:123], v[130:131], v[122:123]
	v_pk_mul_f32 v[124:125], v[132:133], v[124:125]
	v_pk_mul_f32 v[126:127], v[134:135], v[126:127]
	v_pk_fma_f32 v[120:121], v[136:137], v[112:113], v[120:121]
	v_pk_fma_f32 v[122:123], v[138:139], v[114:115], v[122:123]
	v_pk_fma_f32 v[124:125], v[140:141], v[116:117], v[124:125]
	v_pk_fma_f32 v[126:127], v[142:143], v[118:119], v[126:127]
	v_pk_fma_f32 v[120:121], v[144:145], v[96:97], v[120:121]
	v_pk_fma_f32 v[122:123], v[146:147], v[98:99], v[122:123]
	v_pk_fma_f32 v[124:125], v[148:149], v[100:101], v[124:125]
	v_pk_fma_f32 v[126:127], v[150:151], v[102:103], v[126:127]
	v_pk_mul_f32 v[152:153], v[120:121], s[30:31]
	v_pk_mul_f32 v[154:155], v[122:123], s[30:31]
	v_pk_mul_f32 v[164:165], v[124:125], s[30:31]
	v_pk_mul_f32 v[166:167], v[126:127], s[30:31]
	v_pk_mul_f32 v[120:121], v[104:105], v[120:121]
	v_pk_mul_f32 v[122:123], v[106:107], v[122:123]
	v_pk_mul_f32 v[124:125], v[108:109], v[124:125]
	v_pk_mul_f32 v[126:127], v[110:111], v[126:127]
	v_exp_f32_e32 v152, v152
	v_exp_f32_e32 v153, v153
	v_exp_f32_e32 v154, v154
	v_exp_f32_e32 v155, v155
	v_exp_f32_e32 v164, v164
	v_exp_f32_e32 v165, v165
	v_exp_f32_e32 v166, v166
	v_exp_f32_e32 v167, v167
	v_pk_add_f32 v[152:153], v[152:153], 1.0 op_sel_hi:[1,0]
	v_pk_add_f32 v[154:155], v[154:155], 1.0 op_sel_hi:[1,0]
	v_pk_add_f32 v[164:165], v[164:165], 1.0 op_sel_hi:[1,0]
	v_pk_add_f32 v[166:167], v[166:167], 1.0 op_sel_hi:[1,0]
	v_rcp_f32_e32 v152, v152
	v_rcp_f32_e32 v153, v153
	v_rcp_f32_e32 v154, v154
	v_rcp_f32_e32 v155, v155
	v_rcp_f32_e32 v164, v164
	v_rcp_f32_e32 v165, v165
	v_rcp_f32_e32 v166, v166
	v_rcp_f32_e32 v167, v167
	v_pk_mul_f32 v[120:121], v[120:121], v[152:153]
	v_pk_mul_f32 v[122:123], v[122:123], v[154:155]
	v_pk_mul_f32 v[124:125], v[124:125], v[164:165]
	v_pk_mul_f32 v[126:127], v[126:127], v[166:167]
	v_cvt_pk_bf16_f32 v152, v120, v121
	v_cvt_pk_bf16_f32 v153, v122, v123
	v_cvt_pk_bf16_f32 v154, v124, v125
	v_cvt_pk_bf16_f32 v155, v126, v127
	global_store_dwordx4 v67, v[152:155], s[84:85] offset:0
	global_load_dwordx4 v[128:131], v64, s[6:7] offset:256
	global_load_dwordx4 v[132:135], v64, s[6:7] offset:272
	global_load_dwordx4 v[136:139], v64, s[14:15] offset:256
	global_load_dwordx4 v[140:143], v64, s[14:15] offset:272
	global_load_dwordx4 v[144:147], v64, s[18:19] offset:256
	global_load_dwordx4 v[148:151], v64, s[18:19] offset:272
	s_barrier
	ds_write_b128 v194, v[222:225]
	ds_write_b128 v194, v[68:71] offset:64
	ds_write_b128 v194, v[72:75] offset:8448
	ds_write_b128 v194, v[76:79] offset:8512
	ds_write_b128 v194, v[80:83] offset:16896
	ds_write_b128 v194, v[84:87] offset:16960
	ds_write_b128 v194, v[88:91] offset:25344
	ds_write_b128 v194, v[92:95] offset:25408
	s_waitcnt lgkmcnt(0)
	s_barrier
	ds_read_b128 v[96:99], v197
	ds_read_b128 v[100:103], v197 offset:16
	ds_read_b128 v[104:107], v197 offset:256
	ds_read_b128 v[108:111], v197 offset:272
	ds_read_b128 v[112:115], v196 offset:528
	ds_read_b128 v[116:119], v196 offset:544
	ds_read_b128 v[120:123], v196
	ds_read_b128 v[124:127], v196 offset:16
	s_waitcnt vmcnt(0)
	s_mov_b64 exec, s[42:43]
	s_cbranch_execz .Lffn_f3
	s_waitcnt lgkmcnt(4)
	global_store_dwordx4 v66, v[96:99], s[80:81] offset:256
	global_store_dwordx4 v66, v[100:103], s[80:81] offset:272
	global_store_dwordx4 v66, v[104:107], s[82:83] offset:256
	global_store_dwordx4 v66, v[108:111], s[82:83] offset:272
.Lffn_f3:
	s_mov_b64 exec, -1
	s_waitcnt lgkmcnt(0)
	v_pk_mul_f32 v[120:121], v[128:129], v[120:121]
	v_pk_mul_f32 v[122:123], v[130:131], v[122:123]
	v_pk_mul_f32 v[124:125], v[132:133], v[124:125]
	v_pk_mul_f32 v[126:127], v[134:135], v[126:127]
	v_pk_fma_f32 v[120:121], v[136:137], v[112:113], v[120:121]
	v_pk_fma_f32 v[122:123], v[138:139], v[114:115], v[122:123]
	v_pk_fma_f32 v[124:125], v[140:141], v[116:117], v[124:125]
	v_pk_fma_f32 v[126:127], v[142:143], v[118:119], v[126:127]
	v_pk_fma_f32 v[120:121], v[144:145], v[96:97], v[120:121]
	v_pk_fma_f32 v[122:123], v[146:147], v[98:99], v[122:123]
	v_pk_fma_f32 v[124:125], v[148:149], v[100:101], v[124:125]
	v_pk_fma_f32 v[126:127], v[150:151], v[102:103], v[126:127]
	v_pk_mul_f32 v[152:153], v[120:121], s[30:31]
	v_pk_mul_f32 v[154:155], v[122:123], s[30:31]
	v_pk_mul_f32 v[164:165], v[124:125], s[30:31]
	v_pk_mul_f32 v[166:167], v[126:127], s[30:31]
	v_pk_mul_f32 v[120:121], v[104:105], v[120:121]
	v_pk_mul_f32 v[122:123], v[106:107], v[122:123]
	v_pk_mul_f32 v[124:125], v[108:109], v[124:125]
	v_pk_mul_f32 v[126:127], v[110:111], v[126:127]
	v_exp_f32_e32 v152, v152
	v_exp_f32_e32 v153, v153
	v_exp_f32_e32 v154, v154
	v_exp_f32_e32 v155, v155
	v_exp_f32_e32 v164, v164
	v_exp_f32_e32 v165, v165
	v_exp_f32_e32 v166, v166
	v_exp_f32_e32 v167, v167
	v_pk_add_f32 v[152:153], v[152:153], 1.0 op_sel_hi:[1,0]
	v_pk_add_f32 v[154:155], v[154:155], 1.0 op_sel_hi:[1,0]
	v_pk_add_f32 v[164:165], v[164:165], 1.0 op_sel_hi:[1,0]
	v_pk_add_f32 v[166:167], v[166:167], 1.0 op_sel_hi:[1,0]
	v_rcp_f32_e32 v152, v152
	v_rcp_f32_e32 v153, v153
	v_rcp_f32_e32 v154, v154
	v_rcp_f32_e32 v155, v155
	v_rcp_f32_e32 v164, v164
	v_rcp_f32_e32 v165, v165
	v_rcp_f32_e32 v166, v166
	v_rcp_f32_e32 v167, v167
	v_pk_mul_f32 v[120:121], v[120:121], v[152:153]
	v_pk_mul_f32 v[122:123], v[122:123], v[154:155]
	v_pk_mul_f32 v[124:125], v[124:125], v[164:165]
	v_pk_mul_f32 v[126:127], v[126:127], v[166:167]
	v_cvt_pk_bf16_f32 v152, v120, v121
	v_cvt_pk_bf16_f32 v153, v122, v123
	v_cvt_pk_bf16_f32 v154, v124, v125
	v_cvt_pk_bf16_f32 v155, v126, v127
	s_mov_b64 exec, s[40:41]
	global_store_dwordx4 v65, v[152:155], s[84:85] offset:128
	s_mov_b64 exec, -1
	ds_read_b128 v[96:99], v197 offset:33792
	ds_read_b128 v[100:103], v197 offset:33808
	ds_read_b128 v[104:107], v197 offset:34048
	ds_read_b128 v[108:111], v197 offset:34064
	ds_read_b128 v[112:115], v197 offset:33264
	ds_read_b128 v[116:119], v197 offset:33280
	ds_read_b128 v[120:123], v197 offset:32736
	ds_read_b128 v[124:127], v197 offset:32752
	v_add_u32_e32 v67, 0x58000, v65
	s_mov_b64 exec, s[44:45]
	s_cbranch_execz .Lffn_f4
	v_add_u32_e32 v212, 0xfff55800, v66
	s_waitcnt lgkmcnt(6)
	global_store_dwordx4 v212, v[96:99], s[72:73] offset:256
	global_store_dwordx4 v212, v[100:103], s[72:73] offset:272
; DI void stf8(float* p, const F8& f) { *(float4*)p = make_float4(f.v[0], f.v[1], f.v[2], f.v[3]); *(float4*)(p + 4) = make_float4(f.v[4], f.v[5], f.v[6], f.v[7]); }
; DI void stb8(bf16_t* p, const F8& f) { *(uint4*)p = pack8(f); }
; DI float siluf(float x) { return x / (1.f + __expf(-x)); }
; template <int MODE>
; DI void gemm_epilogue(const float* Cs, int m0, int n0, const Epi& ep) {
;     ...
;         const int mt = m0 >> 7, ch0 = (n0 >> 7) * 64, c8 = (tid & 7) * 8, ch = ch0 + c8;
;         const float* cw = ep.c0;
;         const F8 w0 = ldf8(cw + ch), w1 = ldf8(cw + 2816 + ch), w2 = ldf8(cw + 2 * 2816 + ch);
;         const bool defer01 = (m0 < MP) && ((m0 & 8191) != 0);
; #pragma unroll
;         for (int it = 0; it < 2; ++it) {
;             const int i = (tid >> 3) + 64 * it, r = m0 + i;
;             int sq, pos, len; rowinfo(r, sq, pos, len);
;             const F8 g0 = ldf8(Cs + i * LDC + c8), up = ldf8(Cs + i * LDC + 64 + c8);
;             if (i >= 126) stf8(ep.f0 + ((size_t)mt * 2 + (i - 126)) * 2816 + ch, g0);
;             if (i < 2) { stf8(ep.f1 + ((size_t)mt * 2 + i) * 2816 + ch, g0); stf8(ep.f2 + ((size_t)mt * 2 + i) * 2816 + ch, up); }
;             if (pos >= len - 2) {
;                 float* so = sq < 4 ? ep.out + O_PFF + (((size_t)ep.layer * 4 + sq) * 2 + (pos - (len - 2))) * 2816
;                                    : ep.out + O_SFF + (((size_t)ep.layer * 8 + (sq - 4)) * 2 + (pos - (len - 2))) * 2816;
;                 stf8(so + ch, g0);
;             }
;             if (i < 2 && defer01) continue;
;             F8 g1, g2;
;             const float* hist = sq >= 4 ? ep.c1 + ((size_t)ep.layer * 8 + (sq - 4)) * 2 * 2816 + ch : nullptr;
;             if (pos >= 1) g1 = ldf8(Cs + (i - 1) * LDC + c8);
;             else if (hist) g1 = ldf8(hist + 2816);
;             else { for (int e = 0; e < 8; ++e) g1.v[e] = 0.f; }
;             if (pos >= 2) g2 = ldf8(Cs + (i - 2) * LDC + c8);
;             else if (hist) g2 = ldf8(hist + (size_t)pos * 2816);
;             else { for (int e = 0; e < 8; ++e) g2.v[e] = 0.f; }
;             F8 o;
; #pragma unroll
;             for (int e = 0; e < 8; ++e) o.v[e] = siluf(w0.v[e] * g2.v[e] + w1.v[e] * g1.v[e] + w2.v[e] * g0.v[e]) * up.v[e];
;             stb8(ep.b0 + (size_t)r * 2816 + ch, o);
.Lffn_f4:
	s_mov_b64 exec, -1
	s_waitcnt lgkmcnt(0)
	v_pk_mul_f32 v[120:121], v[128:129], v[120:121]
	v_pk_mul_f32 v[122:123], v[130:131], v[122:123]
	v_pk_mul_f32 v[124:125], v[132:133], v[124:125]
	v_pk_mul_f32 v[126:127], v[134:135], v[126:127]
	v_pk_fma_f32 v[120:121], v[136:137], v[112:113], v[120:121]
	v_pk_fma_f32 v[122:123], v[138:139], v[114:115], v[122:123]
	v_pk_fma_f32 v[124:125], v[140:141], v[116:117], v[124:125]
	v_pk_fma_f32 v[126:127], v[142:143], v[118:119], v[126:127]
	v_pk_fma_f32 v[120:121], v[144:145], v[96:97], v[120:121]
	v_pk_fma_f32 v[122:123], v[146:147], v[98:99], v[122:123]
	v_pk_fma_f32 v[124:125], v[148:149], v[100:101], v[124:125]
	v_pk_fma_f32 v[126:127], v[150:151], v[102:103], v[126:127]
	v_pk_mul_f32 v[152:153], v[120:121], s[30:31]
	v_pk_mul_f32 v[154:155], v[122:123], s[30:31]
	v_pk_mul_f32 v[164:165], v[124:125], s[30:31]
	v_pk_mul_f32 v[166:167], v[126:127], s[30:31]
	v_pk_mul_f32 v[120:121], v[104:105], v[120:121]
	v_pk_mul_f32 v[122:123], v[106:107], v[122:123]
	v_pk_mul_f32 v[124:125], v[108:109], v[124:125]
	v_pk_mul_f32 v[126:127], v[110:111], v[126:127]
	v_exp_f32_e32 v152, v152
	v_exp_f32_e32 v153, v153
	v_exp_f32_e32 v154, v154
	v_exp_f32_e32 v155, v155
	v_exp_f32_e32 v164, v164
	v_exp_f32_e32 v165, v165
	v_exp_f32_e32 v166, v166
	v_exp_f32_e32 v167, v167
	v_pk_add_f32 v[152:153], v[152:153], 1.0 op_sel_hi:[1,0]
	v_pk_add_f32 v[154:155], v[154:155], 1.0 op_sel_hi:[1,0]
	v_pk_add_f32 v[164:165], v[164:165], 1.0 op_sel_hi:[1,0]
	v_pk_add_f32 v[166:167], v[166:167], 1.0 op_sel_hi:[1,0]
	v_rcp_f32_e32 v152, v152
	v_rcp_f32_e32 v153, v153
	v_rcp_f32_e32 v154, v154
	v_rcp_f32_e32 v155, v155
	v_rcp_f32_e32 v164, v164
	v_rcp_f32_e32 v165, v165
	v_rcp_f32_e32 v166, v166
	v_rcp_f32_e32 v167, v167
	v_pk_mul_f32 v[120:121], v[120:121], v[152:153]
	v_pk_mul_f32 v[122:123], v[122:123], v[154:155]
	v_pk_mul_f32 v[124:125], v[124:125], v[164:165]
	v_pk_mul_f32 v[126:127], v[126:127], v[166:167]
	v_cvt_pk_bf16_f32 v152, v120, v121
	v_cvt_pk_bf16_f32 v153, v122, v123
	v_cvt_pk_bf16_f32 v154, v124, v125
	v_cvt_pk_bf16_f32 v155, v126, v127
	global_store_dwordx4 v67, v[152:155], s[84:85] offset:128
	global_load_dwordx4 v[128:131], v64, s[6:7] offset:0
	global_load_dwordx4 v[132:135], v64, s[6:7] offset:16
	global_load_dwordx4 v[136:139], v64, s[14:15] offset:0
	global_load_dwordx4 v[140:143], v64, s[14:15] offset:16
	global_load_dwordx4 v[144:147], v64, s[18:19] offset:0
	global_load_dwordx4 v[148:151], v64, s[18:19] offset:16
	s_barrier
	ds_write_b128 v194, v[32:35]
	ds_write_b128 v194, v[36:39] offset:64
	ds_write_b128 v194, v[40:43] offset:8448
	ds_write_b128 v194, v[44:47] offset:8512
	ds_write_b128 v194, v[48:51] offset:16896
	ds_write_b128 v194, v[52:55] offset:16960
	ds_write_b128 v194, v[56:59] offset:25344
	ds_write_b128 v194, v[60:63] offset:25408
	s_waitcnt lgkmcnt(0)
	s_barrier
	ds_read_b128 v[96:99], v197
	ds_read_b128 v[100:103], v197 offset:16
	ds_read_b128 v[104:107], v197 offset:256
	ds_read_b128 v[108:111], v197 offset:272
	ds_read_b128 v[112:115], v196 offset:528
	ds_read_b128 v[116:119], v196 offset:544
	ds_read_b128 v[120:123], v196
	ds_read_b128 v[124:127], v196 offset:16
	v_add_u32_e32 v67, 0xb0000, v65
	s_waitcnt vmcnt(0)
	s_mov_b64 exec, s[42:43]
	s_cbranch_execz .Lffn_f5
	v_add_u32_e32 v212, 0x5800, v66
	s_waitcnt lgkmcnt(4)
	global_store_dwordx4 v212, v[96:99], s[80:81] offset:0
	global_store_dwordx4 v212, v[100:103], s[80:81] offset:16
	global_store_dwordx4 v212, v[104:107], s[82:83] offset:0
	global_store_dwordx4 v212, v[108:111], s[82:83] offset:16
.Lffn_f5:
	s_mov_b64 exec, -1
	s_waitcnt lgkmcnt(0)
	v_pk_mul_f32 v[120:121], v[128:129], v[120:121]
	v_pk_mul_f32 v[122:123], v[130:131], v[122:123]
	v_pk_mul_f32 v[124:125], v[132:133], v[124:125]
	v_pk_mul_f32 v[126:127], v[134:135], v[126:127]
	v_pk_fma_f32 v[120:121], v[136:137], v[112:113], v[120:121]
	v_pk_fma_f32 v[122:123], v[138:139], v[114:115], v[122:123]
	v_pk_fma_f32 v[124:125], v[140:141], v[116:117], v[124:125]
	v_pk_fma_f32 v[126:127], v[142:143], v[118:119], v[126:127]
	v_pk_fma_f32 v[120:121], v[144:145], v[96:97], v[120:121]
	v_pk_fma_f32 v[122:123], v[146:147], v[98:99], v[122:123]
	v_pk_fma_f32 v[124:125], v[148:149], v[100:101], v[124:125]
	v_pk_fma_f32 v[126:127], v[150:151], v[102:103], v[126:127]
	v_pk_mul_f32 v[152:153], v[120:121], s[30:31]
	v_pk_mul_f32 v[154:155], v[122:123], s[30:31]
	v_pk_mul_f32 v[164:165], v[124:125], s[30:31]
	v_pk_mul_f32 v[166:167], v[126:127], s[30:31]
	v_pk_mul_f32 v[120:121], v[104:105], v[120:121]
	v_pk_mul_f32 v[122:123], v[106:107], v[122:123]
	v_pk_mul_f32 v[124:125], v[108:109], v[124:125]
	v_pk_mul_f32 v[126:127], v[110:111], v[126:127]
	v_exp_f32_e32 v152, v152
	v_exp_f32_e32 v153, v153
	v_exp_f32_e32 v154, v154
	v_exp_f32_e32 v155, v155
	v_exp_f32_e32 v164, v164
	v_exp_f32_e32 v165, v165
	v_exp_f32_e32 v166, v166
	v_exp_f32_e32 v167, v167
	v_pk_add_f32 v[152:153], v[152:153], 1.0 op_sel_hi:[1,0]
	v_pk_add_f32 v[154:155], v[154:155], 1.0 op_sel_hi:[1,0]
	v_pk_add_f32 v[164:165], v[164:165], 1.0 op_sel_hi:[1,0]
	v_pk_add_f32 v[166:167], v[166:167], 1.0 op_sel_hi:[1,0]
	v_rcp_f32_e32 v152, v152
	v_rcp_f32_e32 v153, v153
	v_rcp_f32_e32 v154, v154
	v_rcp_f32_e32 v155, v155
	v_rcp_f32_e32 v164, v164
	v_rcp_f32_e32 v165, v165
	v_rcp_f32_e32 v166, v166
	v_rcp_f32_e32 v167, v167
	v_pk_mul_f32 v[120:121], v[120:121], v[152:153]
	v_pk_mul_f32 v[122:123], v[122:123], v[154:155]
	v_pk_mul_f32 v[124:125], v[124:125], v[164:165]
	v_pk_mul_f32 v[126:127], v[126:127], v[166:167]
	v_cvt_pk_bf16_f32 v152, v120, v121
	v_cvt_pk_bf16_f32 v153, v122, v123
	v_cvt_pk_bf16_f32 v154, v124, v125
	v_cvt_pk_bf16_f32 v155, v126, v127
	s_mov_b64 exec, s[40:41]
	global_store_dwordx4 v67, v[152:155], s[84:85] offset:0
	s_mov_b64 exec, -1
	ds_read_b128 v[96:99], v197 offset:33792
	ds_read_b128 v[100:103], v197 offset:33808
	ds_read_b128 v[104:107], v197 offset:34048
	ds_read_b128 v[108:111], v197 offset:34064
	ds_read_b128 v[112:115], v197 offset:33264
	ds_read_b128 v[116:119], v197 offset:33280
	ds_read_b128 v[120:123], v197 offset:32736
	ds_read_b128 v[124:127], v197 offset:32752
	v_add_u32_e32 v67, 0x108000, v65
	s_mov_b64 exec, s[44:45]
	s_cbranch_execz .Lffn_f6
	v_add_u32_e32 v212, 0xfff5b000, v66
	s_waitcnt lgkmcnt(6)
	global_store_dwordx4 v212, v[96:99], s[72:73] offset:0
	global_store_dwordx4 v212, v[100:103], s[72:73] offset:16
; DI void stf8(float* p, const F8& f) { *(float4*)p = make_float4(f.v[0], f.v[1], f.v[2], f.v[3]); *(float4*)(p + 4) = make_float4(f.v[4], f.v[5], f.v[6], f.v[7]); }
; DI void stb8(bf16_t* p, const F8& f) { *(uint4*)p = pack8(f); }
; DI float siluf(float x) { return x / (1.f + __expf(-x)); }
; template <int MODE>
; DI void gemm_epilogue(const float* Cs, int m0, int n0, const Epi& ep) {
;     ...
;         const int mt = m0 >> 7, ch0 = (n0 >> 7) * 64, c8 = (tid & 7) * 8, ch = ch0 + c8;
;         const float* cw = ep.c0;
;         const F8 w0 = ldf8(cw + ch), w1 = ldf8(cw + 2816 + ch), w2 = ldf8(cw + 2 * 2816 + ch);
;         const bool defer01 = (m0 < MP) && ((m0 & 8191) != 0);
; #pragma unroll
;         for (int it = 0; it < 2; ++it) {
;             const int i = (tid >> 3) + 64 * it, r = m0 + i;
;             int sq, pos, len; rowinfo(r, sq, pos, len);
;             const F8 g0 = ldf8(Cs + i * LDC + c8), up = ldf8(Cs + i * LDC + 64 + c8);
;             if (i >= 126) stf8(ep.f0 + ((size_t)mt * 2 + (i - 126)) * 2816 + ch, g0);
;             if (i < 2) { stf8(ep.f1 + ((size_t)mt * 2 + i) * 2816 + ch, g0); stf8(ep.f2 + ((size_t)mt * 2 + i) * 2816 + ch, up); }
;             if (pos >= len - 2) {
;                 float* so = sq < 4 ? ep.out + O_PFF + (((size_t)ep.layer * 4 + sq) * 2 + (pos - (len - 2))) * 2816
;                                    : ep.out + O_SFF + (((size_t)ep.layer * 8 + (sq - 4)) * 2 + (pos - (len - 2))) * 2816;
;                 stf8(so + ch, g0);
;             }
;             if (i < 2 && defer01) continue;
;             F8 g1, g2;
;             const float* hist = sq >= 4 ? ep.c1 + ((size_t)ep.layer * 8 + (sq - 4)) * 2 * 2816 + ch : nullptr;
;             if (pos >= 1) g1 = ldf8(Cs + (i - 1) * LDC + c8);
;             else if (hist) g1 = ldf8(hist + 2816);
;             else { for (int e = 0; e < 8; ++e) g1.v[e] = 0.f; }
;             if (pos >= 2) g2 = ldf8(Cs + (i - 2) * LDC + c8);
;             else if (hist) g2 = ldf8(hist + (size_t)pos * 2816);
;             else { for (int e = 0; e < 8; ++e) g2.v[e] = 0.f; }
;             F8 o;
; #pragma unroll
;             for (int e = 0; e < 8; ++e) o.v[e] = siluf(w0.v[e] * g2.v[e] + w1.v[e] * g1.v[e] + w2.v[e] * g0.v[e]) * up.v[e];
;             stb8(ep.b0 + (size_t)r * 2816 + ch, o);
.Lffn_f6:
	s_mov_b64 exec, -1
	s_waitcnt lgkmcnt(0)
	v_pk_mul_f32 v[120:121], v[128:129], v[120:121]
	v_pk_mul_f32 v[122:123], v[130:131], v[122:123]
	v_pk_mul_f32 v[124:125], v[132:133], v[124:125]
	v_pk_mul_f32 v[126:127], v[134:135], v[126:127]
	v_pk_fma_f32 v[120:121], v[136:137], v[112:113], v[120:121]
	v_pk_fma_f32 v[122:123], v[138:139], v[114:115], v[122:123]
	v_pk_fma_f32 v[124:125], v[140:141], v[116:117], v[124:125]
	v_pk_fma_f32 v[126:127], v[142:143], v[118:119], v[126:127]
	v_pk_fma_f32 v[120:121], v[144:145], v[96:97], v[120:121]
	v_pk_fma_f32 v[122:123], v[146:147], v[98:99], v[122:123]
	v_pk_fma_f32 v[124:125], v[148:149], v[100:101], v[124:125]
	v_pk_fma_f32 v[126:127], v[150:151], v[102:103], v[126:127]
	v_pk_mul_f32 v[152:153], v[120:121], s[30:31]
	v_pk_mul_f32 v[154:155], v[122:123], s[30:31]
	v_pk_mul_f32 v[164:165], v[124:125], s[30:31]
	v_pk_mul_f32 v[166:167], v[126:127], s[30:31]
	v_pk_mul_f32 v[120:121], v[104:105], v[120:121]
	v_pk_mul_f32 v[122:123], v[106:107], v[122:123]
	v_pk_mul_f32 v[124:125], v[108:109], v[124:125]
	v_pk_mul_f32 v[126:127], v[110:111], v[126:127]
	v_exp_f32_e32 v152, v152
	v_exp_f32_e32 v153, v153
	v_exp_f32_e32 v154, v154
	v_exp_f32_e32 v155, v155
	v_exp_f32_e32 v164, v164
	v_exp_f32_e32 v165, v165
	v_exp_f32_e32 v166, v166
	v_exp_f32_e32 v167, v167
	v_pk_add_f32 v[152:153], v[152:153], 1.0 op_sel_hi:[1,0]
	v_pk_add_f32 v[154:155], v[154:155], 1.0 op_sel_hi:[1,0]
	v_pk_add_f32 v[164:165], v[164:165], 1.0 op_sel_hi:[1,0]
	v_pk_add_f32 v[166:167], v[166:167], 1.0 op_sel_hi:[1,0]
	v_rcp_f32_e32 v152, v152
	v_rcp_f32_e32 v153, v153
	v_rcp_f32_e32 v154, v154
	v_rcp_f32_e32 v155, v155
	v_rcp_f32_e32 v164, v164
	v_rcp_f32_e32 v165, v165
	v_rcp_f32_e32 v166, v166
	v_rcp_f32_e32 v167, v167
	v_pk_mul_f32 v[120:121], v[120:121], v[152:153]
	v_pk_mul_f32 v[122:123], v[122:123], v[154:155]
	v_pk_mul_f32 v[124:125], v[124:125], v[164:165]
	v_pk_mul_f32 v[126:127], v[126:127], v[166:167]
	v_cvt_pk_bf16_f32 v152, v120, v121
	v_cvt_pk_bf16_f32 v153, v122, v123
	v_cvt_pk_bf16_f32 v154, v124, v125
	v_cvt_pk_bf16_f32 v155, v126, v127
	global_store_dwordx4 v67, v[152:155], s[84:85] offset:0
	global_load_dwordx4 v[128:131], v64, s[6:7] offset:256
	global_load_dwordx4 v[132:135], v64, s[6:7] offset:272
	global_load_dwordx4 v[136:139], v64, s[14:15] offset:256
	global_load_dwordx4 v[140:143], v64, s[14:15] offset:272
	global_load_dwordx4 v[144:147], v64, s[18:19] offset:256
	global_load_dwordx4 v[148:151], v64, s[18:19] offset:272
	s_barrier
	ds_write_b128 v194, v[0:3]
	ds_write_b128 v194, v[4:7] offset:64
	ds_write_b128 v194, v[8:11] offset:8448
	ds_write_b128 v194, v[12:15] offset:8512
	ds_write_b128 v194, v[16:19] offset:16896
	ds_write_b128 v194, v[20:23] offset:16960
	ds_write_b128 v194, v[24:27] offset:25344
	ds_write_b128 v194, v[28:31] offset:25408
	s_waitcnt lgkmcnt(0)
	s_barrier
	ds_read_b128 v[96:99], v197
	ds_read_b128 v[100:103], v197 offset:16
	ds_read_b128 v[104:107], v197 offset:256
	ds_read_b128 v[108:111], v197 offset:272
	ds_read_b128 v[112:115], v196 offset:528
	ds_read_b128 v[116:119], v196 offset:544
	ds_read_b128 v[120:123], v196
	ds_read_b128 v[124:127], v196 offset:16
	v_add_u32_e32 v67, 0xb0000, v65
	s_waitcnt vmcnt(0)
	s_mov_b64 exec, s[42:43]
	s_cbranch_execz .Lffn_f7
	v_add_u32_e32 v212, 0x5800, v66
	s_waitcnt lgkmcnt(4)
	global_store_dwordx4 v212, v[96:99], s[80:81] offset:256
	global_store_dwordx4 v212, v[100:103], s[80:81] offset:272
	global_store_dwordx4 v212, v[104:107], s[82:83] offset:256
	global_store_dwordx4 v212, v[108:111], s[82:83] offset:272
; DI void stf8(float* p, const F8& f) { *(float4*)p = make_float4(f.v[0], f.v[1], f.v[2], f.v[3]); *(float4*)(p + 4) = make_float4(f.v[4], f.v[5], f.v[6], f.v[7]); }
; DI void stb8(bf16_t* p, const F8& f) { *(uint4*)p = pack8(f); }
; DI float siluf(float x) { return x / (1.f + __expf(-x)); }
; template <int MODE>
; DI void gemm_epilogue(const float* Cs, int m0, int n0, const Epi& ep) {
;     ...
;         const int mt = m0 >> 7, ch0 = (n0 >> 7) * 64, c8 = (tid & 7) * 8, ch = ch0 + c8;
;         const float* cw = ep.c0;
;         const F8 w0 = ldf8(cw + ch), w1 = ldf8(cw + 2816 + ch), w2 = ldf8(cw + 2 * 2816 + ch);
;         const bool defer01 = (m0 < MP) && ((m0 & 8191) != 0);
; #pragma unroll
;         for (int it = 0; it < 2; ++it) {
;             const int i = (tid >> 3) + 64 * it, r = m0 + i;
;             int sq, pos, len; rowinfo(r, sq, pos, len);
;             const F8 g0 = ldf8(Cs + i * LDC + c8), up = ldf8(Cs + i * LDC + 64 + c8);
;             if (i >= 126) stf8(ep.f0 + ((size_t)mt * 2 + (i - 126)) * 2816 + ch, g0);
;             if (i < 2) { stf8(ep.f1 + ((size_t)mt * 2 + i) * 2816 + ch, g0); stf8(ep.f2 + ((size_t)mt * 2 + i) * 2816 + ch, up); }
;             if (pos >= len - 2) {
;                 float* so = sq < 4 ? ep.out + O_PFF + (((size_t)ep.layer * 4 + sq) * 2 + (pos - (len - 2))) * 2816
;                                    : ep.out + O_SFF + (((size_t)ep.layer * 8 + (sq - 4)) * 2 + (pos - (len - 2))) * 2816;
;                 stf8(so + ch, g0);
;             }
;             if (i < 2 && defer01) continue;
;             F8 g1, g2;
;             const float* hist = sq >= 4 ? ep.c1 + ((size_t)ep.layer * 8 + (sq - 4)) * 2 * 2816 + ch : nullptr;
;             if (pos >= 1) g1 = ldf8(Cs + (i - 1) * LDC + c8);
;             else if (hist) g1 = ldf8(hist + 2816);
;             else { for (int e = 0; e < 8; ++e) g1.v[e] = 0.f; }
;             if (pos >= 2) g2 = ldf8(Cs + (i - 2) * LDC + c8);
;             else if (hist) g2 = ldf8(hist + (size_t)pos * 2816);
;             else { for (int e = 0; e < 8; ++e) g2.v[e] = 0.f; }
;             F8 o;
; #pragma unroll
;             for (int e = 0; e < 8; ++e) o.v[e] = siluf(w0.v[e] * g2.v[e] + w1.v[e] * g1.v[e] + w2.v[e] * g0.v[e]) * up.v[e];
;             stb8(ep.b0 + (size_t)r * 2816 + ch, o);
.Lffn_f7:
	s_mov_b64 exec, -1
	s_waitcnt lgkmcnt(0)
	v_pk_mul_f32 v[120:121], v[128:129], v[120:121]
	v_pk_mul_f32 v[122:123], v[130:131], v[122:123]
	v_pk_mul_f32 v[124:125], v[132:133], v[124:125]
	v_pk_mul_f32 v[126:127], v[134:135], v[126:127]
	v_pk_fma_f32 v[120:121], v[136:137], v[112:113], v[120:121]
	v_pk_fma_f32 v[122:123], v[138:139], v[114:115], v[122:123]
	v_pk_fma_f32 v[124:125], v[140:141], v[116:117], v[124:125]
	v_pk_fma_f32 v[126:127], v[142:143], v[118:119], v[126:127]
	v_pk_fma_f32 v[120:121], v[144:145], v[96:97], v[120:121]
	v_pk_fma_f32 v[122:123], v[146:147], v[98:99], v[122:123]
	v_pk_fma_f32 v[124:125], v[148:149], v[100:101], v[124:125]
	v_pk_fma_f32 v[126:127], v[150:151], v[102:103], v[126:127]
	v_pk_mul_f32 v[152:153], v[120:121], s[30:31]
	v_pk_mul_f32 v[154:155], v[122:123], s[30:31]
	v_pk_mul_f32 v[164:165], v[124:125], s[30:31]
	v_pk_mul_f32 v[166:167], v[126:127], s[30:31]
	v_pk_mul_f32 v[120:121], v[104:105], v[120:121]
	v_pk_mul_f32 v[122:123], v[106:107], v[122:123]
	v_pk_mul_f32 v[124:125], v[108:109], v[124:125]
	v_pk_mul_f32 v[126:127], v[110:111], v[126:127]
	v_exp_f32_e32 v152, v152
	v_exp_f32_e32 v153, v153
	v_exp_f32_e32 v154, v154
	v_exp_f32_e32 v155, v155
	v_exp_f32_e32 v164, v164
	v_exp_f32_e32 v165, v165
	v_exp_f32_e32 v166, v166
	v_exp_f32_e32 v167, v167
	v_pk_add_f32 v[152:153], v[152:153], 1.0 op_sel_hi:[1,0]
	v_pk_add_f32 v[154:155], v[154:155], 1.0 op_sel_hi:[1,0]
	v_pk_add_f32 v[164:165], v[164:165], 1.0 op_sel_hi:[1,0]
	v_pk_add_f32 v[166:167], v[166:167], 1.0 op_sel_hi:[1,0]
	v_rcp_f32_e32 v152, v152
	v_rcp_f32_e32 v153, v153
	v_rcp_f32_e32 v154, v154
	v_rcp_f32_e32 v155, v155
	v_rcp_f32_e32 v164, v164
	v_rcp_f32_e32 v165, v165
	v_rcp_f32_e32 v166, v166
	v_rcp_f32_e32 v167, v167
	v_pk_mul_f32 v[120:121], v[120:121], v[152:153]
	v_pk_mul_f32 v[122:123], v[122:123], v[154:155]
	v_pk_mul_f32 v[124:125], v[124:125], v[164:165]
	v_pk_mul_f32 v[126:127], v[126:127], v[166:167]
	v_cvt_pk_bf16_f32 v152, v120, v121
	v_cvt_pk_bf16_f32 v153, v122, v123
	v_cvt_pk_bf16_f32 v154, v124, v125
	v_cvt_pk_bf16_f32 v155, v126, v127
	s_mov_b64 exec, s[40:41]
	global_store_dwordx4 v67, v[152:155], s[84:85] offset:128
	s_mov_b64 exec, -1
	ds_read_b128 v[96:99], v197 offset:33792
	ds_read_b128 v[100:103], v197 offset:33808
	ds_read_b128 v[104:107], v197 offset:34048
	ds_read_b128 v[108:111], v197 offset:34064
	ds_read_b128 v[112:115], v197 offset:33264
	ds_read_b128 v[116:119], v197 offset:33280
	ds_read_b128 v[120:123], v197 offset:32736
	ds_read_b128 v[124:127], v197 offset:32752
	v_add_u32_e32 v67, 0x108000, v65
	s_mov_b64 exec, s[44:45]
	s_cbranch_execz .Lffn_f8
	v_add_u32_e32 v212, 0xfff5b000, v66
	s_waitcnt lgkmcnt(6)
	global_store_dwordx4 v212, v[96:99], s[72:73] offset:256
	global_store_dwordx4 v212, v[100:103], s[72:73] offset:272
.Lffn_f8:
	s_mov_b64 exec, -1
	s_waitcnt lgkmcnt(0)
	v_pk_mul_f32 v[120:121], v[128:129], v[120:121]
	v_pk_mul_f32 v[122:123], v[130:131], v[122:123]
	v_pk_mul_f32 v[124:125], v[132:133], v[124:125]
	v_pk_mul_f32 v[126:127], v[134:135], v[126:127]
	v_pk_fma_f32 v[120:121], v[136:137], v[112:113], v[120:121]
	v_pk_fma_f32 v[122:123], v[138:139], v[114:115], v[122:123]
	v_pk_fma_f32 v[124:125], v[140:141], v[116:117], v[124:125]
	v_pk_fma_f32 v[126:127], v[142:143], v[118:119], v[126:127]
	v_pk_fma_f32 v[120:121], v[144:145], v[96:97], v[120:121]
	v_pk_fma_f32 v[122:123], v[146:147], v[98:99], v[122:123]
	v_pk_fma_f32 v[124:125], v[148:149], v[100:101], v[124:125]
	v_pk_fma_f32 v[126:127], v[150:151], v[102:103], v[126:127]
	v_pk_mul_f32 v[152:153], v[120:121], s[30:31]
	v_pk_mul_f32 v[154:155], v[122:123], s[30:31]
	v_pk_mul_f32 v[164:165], v[124:125], s[30:31]
	v_pk_mul_f32 v[166:167], v[126:127], s[30:31]
	v_pk_mul_f32 v[120:121], v[104:105], v[120:121]
	v_pk_mul_f32 v[122:123], v[106:107], v[122:123]
	v_pk_mul_f32 v[124:125], v[108:109], v[124:125]
	v_pk_mul_f32 v[126:127], v[110:111], v[126:127]
	v_exp_f32_e32 v152, v152
	v_exp_f32_e32 v153, v153
	v_exp_f32_e32 v154, v154
	v_exp_f32_e32 v155, v155
	v_exp_f32_e32 v164, v164
	v_exp_f32_e32 v165, v165
	v_exp_f32_e32 v166, v166
	v_exp_f32_e32 v167, v167
	v_pk_add_f32 v[152:153], v[152:153], 1.0 op_sel_hi:[1,0]
	v_pk_add_f32 v[154:155], v[154:155], 1.0 op_sel_hi:[1,0]
	v_pk_add_f32 v[164:165], v[164:165], 1.0 op_sel_hi:[1,0]
	v_pk_add_f32 v[166:167], v[166:167], 1.0 op_sel_hi:[1,0]
	v_rcp_f32_e32 v152, v152
	v_rcp_f32_e32 v153, v153
	v_rcp_f32_e32 v154, v154
	v_rcp_f32_e32 v155, v155
	v_rcp_f32_e32 v164, v164
	v_rcp_f32_e32 v165, v165
	v_rcp_f32_e32 v166, v166
	v_rcp_f32_e32 v167, v167
	v_pk_mul_f32 v[120:121], v[120:121], v[152:153]
	v_pk_mul_f32 v[122:123], v[122:123], v[154:155]
	v_pk_mul_f32 v[124:125], v[124:125], v[164:165]
	v_pk_mul_f32 v[126:127], v[126:127], v[166:167]
	v_cvt_pk_bf16_f32 v152, v120, v121
	v_cvt_pk_bf16_f32 v153, v122, v123
	v_cvt_pk_bf16_f32 v154, v124, v125
	v_cvt_pk_bf16_f32 v155, v126, v127
	global_store_dwordx4 v67, v[152:155], s[84:85] offset:128
	s_mov_b64 s[0:1], -1
	s_branch .LBB0_1142
